# GEMM phases proj/outproj: epilogue code at s_setprio 1, k-loop at 0 (on top of filler priority 3 in mix)
# baseline (speedup 1.0000x reference)
.LBB0_13:
	s_setprio 0
	v_writelane_b32 v254, s20, 53
	s_add_i32 s0, s20, -1
	s_mul_hi_i32 s1, s0, 0x92492493
	s_add_i32 s1, s1, s0
	s_lshr_b32 s2, s1, 31
	s_ashr_i32 s1, s1, 2
	s_add_i32 s60, s1, s2
	s_mul_i32 s1, s60, 7
	v_writelane_b32 v254, s21, 54
	s_sub_i32 s4, s0, s1
	s_mov_b64 s[0:1], -1
	s_mov_b64 s[2:3], 0
	v_writelane_b32 v254, s4, 55
	s_cmp_lt_i32 s4, 3
	s_mov_b64 s[44:45], 0
	s_cbranch_scc1 .LBB0_237
	v_readlane_b32 s0, v254, 55
	s_cmp_gt_i32 s0, 3
	s_cbranch_scc0 .LBB0_76
	s_cmp_gt_i32 s0, 4
	s_cbranch_scc0 .LBB0_77
	s_cmp_eq_u32 s0, 5
	s_mov_b64 s[44:45], -1
	s_cbranch_scc0 .LBB0_79
	v_readlane_b32 s0, v251, 2
	v_readlane_b32 s1, v251, 3
	v_mov_b32_e32 v150, v218
	s_andn2_b64 vcc, exec, s[0:1]
	s_cbranch_vccnz .LBB0_78
	v_ashrrev_i32_e32 v151, 3, v150
	s_ashr_i32 s61, s60, 31
	v_readlane_b32 s6, v251, 6
	s_lshl_b64 s[0:1], s[60:61], 22
	v_readlane_b32 s4, v251, 4
	v_add_u32_e32 v2, s6, v151
	s_add_u32 s4, s4, s0
	v_readlane_b32 s5, v251, 5
	v_ashrrev_i32_e32 v3, 31, v2
	v_readlane_b32 s6, v251, 8
	v_lshlrev_b32_e32 v130, 4, v150
	s_addc_u32 s5, s5, s1
	v_lshlrev_b64 v[2:3], 11, v[2:3]
	v_add_u32_e32 v6, s6, v151
	s_waitcnt lgkmcnt(0)
	v_and_b32_e32 v0, 0x70, v130
	v_lshl_add_u64 v[2:3], s[4:5], 0, v[2:3]
	v_ashrrev_i32_e32 v7, 31, v6
	v_readlane_b32 s6, v250, 62
	v_lshl_add_u64 v[2:3], v[2:3], 0, v[0:1]
	s_mov_b32 s8, 0x30000
	v_lshlrev_b64 v[6:7], 11, v[6:7]
	v_readlane_b32 s7, v250, 63
	v_add_co_u32_e32 v4, vcc, s8, v2
	s_nop 0
	v_lshl_add_u64 v[6:7], s[6:7], 0, v[6:7]
	v_addc_co_u32_e32 v5, vcc, 0, v3, vcc
	v_lshl_add_u64 v[6:7], v[6:7], 0, v[0:1]
	v_add_co_u32_e32 v8, vcc, s8, v6
	s_mov_b32 s8, 0x10000
	s_nop 0
	v_addc_co_u32_e32 v9, vcc, 0, v7, vcc
	v_add_co_u32_e32 v10, vcc, s55, v2
	v_lshl_add_u64 v[132:133], s[6:7], 0, v[0:1]
	s_nop 0
	v_addc_co_u32_e32 v11, vcc, 0, v3, vcc
	v_add_co_u32_e32 v12, vcc, s55, v6
	v_lshl_add_u64 v[136:137], s[4:5], 0, v[0:1]
	s_nop 0
	v_addc_co_u32_e32 v13, vcc, 0, v7, vcc
	global_load_dwordx4 v[82:85], v[10:11], off
	global_load_dwordx4 v[86:89], v[12:13], off
	v_add_co_u32_e32 v10, vcc, s8, v2
	s_movk_i32 s4, 0x204
	s_nop 0
	v_addc_co_u32_e32 v11, vcc, 0, v3, vcc
	v_add_co_u32_e32 v12, vcc, s8, v6
	s_movk_i32 s8, 0x90
	s_nop 0
	v_addc_co_u32_e32 v13, vcc, 0, v7, vcc
	global_load_dwordx4 v[74:77], v[10:11], off
	global_load_dwordx4 v[78:81], v[12:13], off
	global_load_dwordx4 v[94:97], v[4:5], off
	global_load_dwordx4 v[66:69], v[2:3], off
	global_load_dwordx4 v[90:93], v[8:9], off
	global_load_dwordx4 v[70:73], v[6:7], off
	v_mad_u64_u32 v[134:135], s[6:7], v151, s8, v[0:1]
	v_ashrrev_i32_e32 v0, 1, v150
	v_and_b32_e32 v0, 0xffffffc0, v0
	v_and_or_b32 v2, v150, 31, v0
	v_mul_lo_u32 v153, v2, s8
	v_lshrrev_b32_e32 v2, 3, v150
	v_lshrrev_b32_e32 v3, 1, v150
	v_and_or_b32 v0, v2, 4, v0
	v_and_b32_e32 v135, 16, v3
	v_and_b32_e32 v3, 0x5f, v150
	v_mul_lo_u32 v0, v0, s4
	v_ashrrev_i32_e32 v2, 7, v150
	v_mul_u32_u24_e32 v152, 0x90, v3
	v_lshl_add_u32 v154, v3, 2, v0
	v_and_b32_e32 v0, 0x7f, v150
	v_lshlrev_b32_e32 v3, 8, v2
	v_mad_u32_u24 v156, v0, s4, v3
	s_movk_i32 s4, 0x80
	v_cmp_gt_u32_e64 s[42:43], s4, v150
	v_cmp_gt_i32_e64 s[44:45], s4, v150
	v_readlane_b32 s4, v250, 0
	v_readlane_b32 s5, v250, 1
	s_load_dword s4, s[4:5], 0x10
	v_lshlrev_b32_e32 v155, 6, v2
	v_cmp_eq_u32_e64 s[40:41], 1, v2
	v_readlane_b32 s6, v251, 0
	v_add_u32_e32 v2, 0x800, v130
	s_waitcnt lgkmcnt(0)
	s_lshr_b32 s4, s4, 16
	s_cmp_lg_u32 s4, 0
	v_readlane_b32 s7, v251, 1
	v_ashrrev_i32_e32 v3, 31, v2
	s_cselect_b64 s[4:5], -1, 0
	v_lshl_add_u64 v[140:141], v[2:3], 2, s[6:7]
	v_cndmask_b32_e64 v2, 0, 1, s[4:5]
	s_cmp_lg_u64 s[4:5], 0
	v_readlane_b32 s4, v254, 45
	s_addc_u32 s10, s4, 0
	s_lshl_b32 s11, s10, 4
	v_lshlrev_b32_e32 v4, 6, v0
	v_and_b32_e32 v0, 7, v150
	s_add_u32 s0, s94, s0
	v_lshlrev_b32_e32 v0, 4, v0
	s_addc_u32 s1, s95, s1
	v_lshlrev_b32_e32 v5, 6, v150
	v_ashrrev_i32_e32 v131, 31, v130
	v_lshl_add_u64 v[144:145], s[0:1], 0, v[0:1]
	v_readlane_b32 s0, v253, 39
	s_movk_i32 s61, 0x3fff
	s_mov_b32 s71, 0x30000
	v_lshl_add_u64 v[138:139], v[130:131], 2, s[6:7]
	v_lshlrev_b32_e32 v131, 7, v150
	v_lshl_add_u64 v[142:143], s[94:95], 0, v[0:1]
	v_add_u32_e32 v157, s4, v2
	v_mov_b32_e32 v158, s0
	v_add_u32_e32 v159, 0x10200, v4
	v_add_u32_e32 v160, 0x10200, v5
	v_readlane_b32 s12, v251, 7
	s_mov_b32 s13, s0
	v_readlane_b32 s5, v254, 46
	v_readlane_b32 s1, v253, 40
	s_branch .LBB0_32

.LBB0_101:
	s_setprio 0
	s_and_b32 s4, s9, 0xffffff80
	v_add_u32_e32 v2, s4, v146
	v_ashrrev_i32_e32 v3, 31, v2
	v_lshlrev_b64 v[2:3], 11, v[2:3]
	s_and_b32 s4, s8, 0x380
	v_lshl_add_u64 v[142:143], v[138:139], 0, v[2:3]
	v_add_u32_e32 v2, s4, v146
	v_ashrrev_i32_e32 v3, 31, v2
	v_lshlrev_b64 v[2:3], 11, v[2:3]
	v_lshl_add_u64 v[144:145], v[140:141], 0, v[2:3]
	v_mov_b32_e32 v2, 0
	s_mov_b32 s11, s10
	s_mov_b32 s10, 0
	s_mov_b64 s[4:5], 0
	v_mov_b32_e32 v3, v2
	v_mov_b32_e32 v4, v2
	v_mov_b32_e32 v5, v2
	v_mov_b32_e32 v6, v2
	v_mov_b32_e32 v7, v2
	v_mov_b32_e32 v8, v2
	v_mov_b32_e32 v9, v2
	v_mov_b32_e32 v10, v2
	v_mov_b32_e32 v11, v2
	v_mov_b32_e32 v12, v2
	v_mov_b32_e32 v13, v2
	v_mov_b32_e32 v14, v2
	v_mov_b32_e32 v15, v2
	v_mov_b32_e32 v16, v2
	v_mov_b32_e32 v17, v2
	v_mov_b32_e32 v18, v2
	v_mov_b32_e32 v19, v2
	v_mov_b32_e32 v20, v2
	v_mov_b32_e32 v21, v2
	v_mov_b32_e32 v22, v2
	v_mov_b32_e32 v23, v2
	v_mov_b32_e32 v24, v2
	v_mov_b32_e32 v25, v2
	v_mov_b32_e32 v26, v2
	v_mov_b32_e32 v27, v2
	v_mov_b32_e32 v28, v2
	v_mov_b32_e32 v29, v2
	v_mov_b32_e32 v30, v2
	v_mov_b32_e32 v31, v2
	v_mov_b32_e32 v32, v2
	v_mov_b32_e32 v33, v2
	v_mov_b32_e32 v34, v2
	v_mov_b32_e32 v35, v2
	v_mov_b32_e32 v36, v2
	v_mov_b32_e32 v37, v2
	v_mov_b32_e32 v38, v2
	v_mov_b32_e32 v39, v2
	v_mov_b32_e32 v40, v2
	v_mov_b32_e32 v41, v2
	v_mov_b32_e32 v42, v2
	v_mov_b32_e32 v43, v2
	v_mov_b32_e32 v44, v2
	v_mov_b32_e32 v45, v2
	v_mov_b32_e32 v46, v2
	v_mov_b32_e32 v47, v2
	v_mov_b32_e32 v48, v2
	v_mov_b32_e32 v49, v2
	v_mov_b32_e32 v50, v2
	v_mov_b32_e32 v51, v2
	v_mov_b32_e32 v52, v2
	v_mov_b32_e32 v53, v2
	v_mov_b32_e32 v54, v2
	v_mov_b32_e32 v55, v2
	v_mov_b32_e32 v56, v2
	v_mov_b32_e32 v57, v2
	v_mov_b32_e32 v58, v2
	v_mov_b32_e32 v59, v2
	v_mov_b32_e32 v60, v2
	v_mov_b32_e32 v61, v2
	v_mov_b32_e32 v62, v2
	v_mov_b32_e32 v63, v2
	v_mov_b32_e32 v64, v2
	v_mov_b32_e32 v65, v2
	s_waitcnt vmcnt(0)
	v_mov_b32_e32 v98, v86
	v_mov_b32_e32 v99, v87
	v_mov_b32_e32 v100, v88
	v_mov_b32_e32 v101, v89
	v_mov_b32_e32 v106, v94
	v_mov_b32_e32 v107, v95
	v_mov_b32_e32 v108, v96
	s_waitcnt lgkmcnt(0)
	v_mov_b32_e32 v109, v97
	v_mov_b32_e32 v110, v90
	v_mov_b32_e32 v111, v91
	v_mov_b32_e32 v112, v92
	v_mov_b32_e32 v113, v93
	v_mov_b32_e32 v122, v78
	v_mov_b32_e32 v123, v79
	v_mov_b32_e32 v124, v80
	v_mov_b32_e32 v125, v81
	v_mov_b32_e32 v102, v82
	v_mov_b32_e32 v103, v83
	v_mov_b32_e32 v104, v84
	v_mov_b32_e32 v105, v85
	v_mov_b32_e32 v114, v74
	v_mov_b32_e32 v115, v75
	v_mov_b32_e32 v116, v76
	v_mov_b32_e32 v117, v77
	v_mov_b32_e32 v118, v70
	v_mov_b32_e32 v119, v71
	v_mov_b32_e32 v120, v72
	v_mov_b32_e32 v121, v73
	v_mov_b32_e32 v126, v66
	v_mov_b32_e32 v127, v67
	v_mov_b32_e32 v128, v68
	v_mov_b32_e32 v129, v69
	s_barrier
	ds_write_b128 v134, v[86:89]
	ds_write_b128 v134, v[82:85] offset:18432
	ds_write_b128 v134, v[94:97] offset:4608
	ds_write_b128 v134, v[74:77] offset:23040
	ds_write_b128 v134, v[90:93] offset:9216
	ds_write_b128 v134, v[70:73] offset:27648
	ds_write_b128 v134, v[78:81] offset:13824
	ds_write_b128 v134, v[66:69] offset:32256
	s_waitcnt lgkmcnt(0)
	s_barrier
	s_branch .LBB0_103

.LBB0_107:
	s_setprio 1
	v_readlane_b32 s4, v254, 45
	s_add_i32 s10, s11, s4
	v_readlane_b32 s5, v254, 46
	s_cmpk_gt_i32 s10, 0x3ff
	s_cselect_b64 s[4:5], -1, 0
	s_and_b64 vcc, exec, s[4:5]
	s_branch .LBB0_109

.LBB0_445:
	s_setprio 0
	s_mul_hi_i32 s6, s34, 0x66666667
	s_lshr_b32 s7, s6, 31
	s_ashr_i32 s6, s6, 3
	s_add_i32 s6, s6, s7
	s_mul_i32 s7, s6, 20
	s_lshl_b32 s10, s6, 7
	s_sub_i32 s12, s34, s7
	v_add_u32_e32 v2, s10, v148
	v_ashrrev_i32_e32 v3, 31, v2
	v_lshl_add_u32 v4, s12, 7, v148
	v_lshlrev_b64 v[2:3], 11, v[2:3]
	v_ashrrev_i32_e32 v5, 31, v4
	v_lshlrev_b64 v[4:5], 11, v[4:5]
	v_lshl_add_u64 v[142:143], v[138:139], 0, v[2:3]
	v_mov_b32_e32 v2, 0
	v_lshl_add_u64 v[144:145], v[140:141], 0, v[4:5]
	s_mov_b32 s11, 0
	s_mov_b64 s[6:7], 0
	v_mov_b32_e32 v3, v2
	v_mov_b32_e32 v4, v2
	v_mov_b32_e32 v5, v2
	v_mov_b32_e32 v6, v2
	v_mov_b32_e32 v7, v2
	v_mov_b32_e32 v8, v2
	v_mov_b32_e32 v9, v2
	v_mov_b32_e32 v10, v2
	v_mov_b32_e32 v11, v2
	v_mov_b32_e32 v12, v2
	v_mov_b32_e32 v13, v2
	v_mov_b32_e32 v14, v2
	v_mov_b32_e32 v15, v2
	v_mov_b32_e32 v16, v2
	v_mov_b32_e32 v17, v2
	v_mov_b32_e32 v18, v2
	v_mov_b32_e32 v19, v2
	v_mov_b32_e32 v20, v2
	v_mov_b32_e32 v21, v2
	v_mov_b32_e32 v22, v2
	v_mov_b32_e32 v23, v2
	v_mov_b32_e32 v24, v2
	v_mov_b32_e32 v25, v2
	v_mov_b32_e32 v26, v2
	v_mov_b32_e32 v27, v2
	v_mov_b32_e32 v28, v2
	v_mov_b32_e32 v29, v2
	v_mov_b32_e32 v30, v2
	v_mov_b32_e32 v31, v2
	v_mov_b32_e32 v32, v2
	v_mov_b32_e32 v33, v2
	v_mov_b32_e32 v34, v2
	v_mov_b32_e32 v35, v2
	v_mov_b32_e32 v36, v2
	v_mov_b32_e32 v37, v2
	v_mov_b32_e32 v38, v2
	v_mov_b32_e32 v39, v2
	v_mov_b32_e32 v40, v2
	v_mov_b32_e32 v41, v2
	v_mov_b32_e32 v42, v2
	v_mov_b32_e32 v43, v2
	v_mov_b32_e32 v44, v2
	v_mov_b32_e32 v45, v2
	v_mov_b32_e32 v46, v2
	v_mov_b32_e32 v47, v2
	v_mov_b32_e32 v48, v2
	v_mov_b32_e32 v49, v2
	v_mov_b32_e32 v50, v2
	s_waitcnt lgkmcnt(0)
	v_mov_b32_e32 v51, v2
	v_mov_b32_e32 v52, v2
	v_mov_b32_e32 v53, v2
	v_mov_b32_e32 v54, v2
	v_mov_b32_e32 v55, v2
	v_mov_b32_e32 v56, v2
	v_mov_b32_e32 v57, v2
	v_mov_b32_e32 v58, v2
	v_mov_b32_e32 v59, v2
	v_mov_b32_e32 v60, v2
	v_mov_b32_e32 v61, v2
	v_mov_b32_e32 v62, v2
	v_mov_b32_e32 v63, v2
	v_mov_b32_e32 v64, v2
	v_mov_b32_e32 v65, v2
	s_waitcnt vmcnt(0)
	v_mov_b32_e32 v98, v70
	v_mov_b32_e32 v99, v71
	v_mov_b32_e32 v100, v72
	v_mov_b32_e32 v101, v73
	v_mov_b32_e32 v106, v74
	v_mov_b32_e32 v107, v75
	v_mov_b32_e32 v108, v76
	v_mov_b32_e32 v109, v77
	v_mov_b32_e32 v110, v82
	v_mov_b32_e32 v111, v83
	v_mov_b32_e32 v112, v84
	v_mov_b32_e32 v113, v85
	v_mov_b32_e32 v122, v90
	v_mov_b32_e32 v123, v91
	v_mov_b32_e32 v124, v92
	v_mov_b32_e32 v125, v93
	v_mov_b32_e32 v102, v66
	v_mov_b32_e32 v103, v67
	v_mov_b32_e32 v104, v68
	v_mov_b32_e32 v105, v69
	v_mov_b32_e32 v114, v78
	v_mov_b32_e32 v115, v79
	v_mov_b32_e32 v116, v80
	v_mov_b32_e32 v117, v81
	v_mov_b32_e32 v118, v86
	v_mov_b32_e32 v119, v87
	v_mov_b32_e32 v120, v88
	v_mov_b32_e32 v121, v89
	v_mov_b32_e32 v126, v94
	v_mov_b32_e32 v127, v95
	v_mov_b32_e32 v128, v96
	v_mov_b32_e32 v129, v97
	s_barrier
	ds_write_b128 v134, v[70:73]
	ds_write_b128 v134, v[66:69] offset:18432
	ds_write_b128 v134, v[74:77] offset:4608
	ds_write_b128 v134, v[78:81] offset:23040
	ds_write_b128 v134, v[82:85] offset:9216
	ds_write_b128 v134, v[86:89] offset:27648
	ds_write_b128 v134, v[90:93] offset:13824
	ds_write_b128 v134, v[94:97] offset:32256
	s_waitcnt lgkmcnt(0)
	s_barrier
	s_branch .LBB0_447

.LBB0_451:
	s_setprio 1
	v_readlane_b32 s6, v254, 45
	s_add_i32 s34, s34, s6
	v_readlane_b32 s7, v254, 46
	s_cmpk_gt_i32 s34, 0x9ff
	s_cselect_b64 s[6:7], -1, 0
	s_and_b64 vcc, exec, s[6:7]
	s_cbranch_vccnz .LBB0_453
	s_lshr_b32 s8, s12, 2
	s_cmp_eq_u32 s8, 1
	s_cbranch_scc1 .LBB0_453
	s_sub_u32 s8, s12, 10
	s_cmp_lt_u32 s8, 4
	s_cbranch_scc1 .LBB0_453
	s_mul_hi_i32 s8, s34, 0x66666667
	s_lshr_b32 s9, s8, 31
	s_ashr_i32 s8, s8, 3
	s_add_i32 s8, s8, s9
	v_lshl_add_u32 v66, s8, 7, v148
	s_mul_i32 s9, s8, 20
	v_ashrrev_i32_e32 v67, 31, v66
	s_sub_i32 s9, s34, s9
	v_lshlrev_b64 v[66:67], 11, v[66:67]
	v_lshl_add_u64 v[90:91], v[130:131], 0, v[66:67]
	v_lshl_add_u32 v66, s9, 7, v148
	v_ashrrev_i32_e32 v67, 31, v66
	v_lshlrev_b64 v[66:67], 11, v[66:67]
	v_add_co_u32_e32 v74, vcc, 0x10000, v90
	v_lshl_add_u64 v[92:93], v[132:133], 0, v[66:67]
	s_nop 0
	v_addc_co_u32_e32 v75, vcc, 0, v91, vcc
	v_add_co_u32_e32 v78, vcc, 0x10000, v92
	global_load_dwordx4 v[70:73], v[90:91], off
	global_load_dwordx4 v[66:69], v[92:93], off
	v_addc_co_u32_e32 v79, vcc, 0, v93, vcc
	v_add_co_u32_e32 v82, vcc, 0x20000, v90
	global_load_dwordx4 v[74:77], v[74:75], off
	s_nop 0
	global_load_dwordx4 v[78:81], v[78:79], off
	v_addc_co_u32_e32 v83, vcc, 0, v91, vcc
	v_add_co_u32_e32 v86, vcc, 0x20000, v92
	s_nop 1
	v_addc_co_u32_e32 v87, vcc, 0, v93, vcc
	v_add_co_u32_e32 v90, vcc, 0x30000, v90
	global_load_dwordx4 v[82:85], v[82:83], off
	s_nop 0
	global_load_dwordx4 v[86:89], v[86:87], off
	v_addc_co_u32_e32 v91, vcc, 0, v91, vcc
	v_add_co_u32_e32 v94, vcc, 0x30000, v92
	s_nop 1
	v_addc_co_u32_e32 v95, vcc, 0, v93, vcc
	global_load_dwordx4 v[90:93], v[90:91], off
	s_nop 0
	global_load_dwordx4 v[94:97], v[94:95], off
